# hmat layer-0 item: the 8 row loads issued together instead of a load-store-load chain
# baseline (speedup 1.0000x reference)
.LBB0_138:
	s_add_i32 s8, s6, 0xfffff000
	s_cmpk_lt_i32 s10, 0x200
	s_waitcnt lgkmcnt(0)
	s_cselect_b32 s11, s37, s39
	s_cselect_b32 s16, s36, s38
	s_ashr_i32 s7, s6, 31
	s_cmpk_lt_i32 s10, 0x200
	s_cselect_b32 s12, s6, s8
	s_cselect_b32 s13, s7, 0
	s_lshr_b32 s8, s8, 10
	s_mulk_i32 s8, 0x1800
	s_addk_i32 s8, 0x1800
	s_cmpk_lt_i32 s10, 0x200
	v_mov_b32_e32 v0, v234
	s_cselect_b32 s8, 0, s8
	s_lshl_b64 s[14:15], s[8:9], 2
	v_lshlrev_b32_e32 v2, 2, v0
	v_ashrrev_i32_e32 v3, 31, v2
	s_add_u32 s14, s30, s14
	v_lshlrev_b64 v[0:1], 2, v[2:3]
	s_addc_u32 s15, s31, s15
	s_lshl_b64 s[12:13], s[12:13], 12
	v_lshl_add_u64 v[12:13], s[14:15], 0, v[0:1]
	s_add_u32 s12, s16, s12
	s_addc_u32 s13, s11, s13
	v_add_co_u32_e32 v14, vcc, s3, v12
	s_add_i32 s14, s6, 1
	s_nop 0
	v_addc_co_u32_e32 v15, vcc, 0, v13, vcc
	global_load_dwordx4 v[8:11], v[12:13], off
	global_load_dwordx4 v[4:7], v[14:15], off
	v_lshl_add_u64 v[2:3], v[2:3], 1, s[4:5]
	s_add_i32 s14, s6, 0
	s_add_i32 s7, s6, 0xfffff000
	s_ashr_i32 s15, s14, 31
	s_cmpk_lt_i32 s14, 0x1000
	s_cselect_b32 s8, s36, s38
	s_cselect_b32 s13, s15, 0
	s_cselect_b32 s12, s14, s7
	s_cselect_b32 s7, s37, s39
	s_lshl_b64 s[12:13], s[12:13], 12
	s_add_u32 s12, s8, s12
	s_addc_u32 s13, s7, s13
	v_lshl_add_u64 v[18:19], s[12:13], 0, v[0:1]
	global_load_dwordx4 v[20:23], v[18:19], off
	s_add_i32 s14, s6, 1
	s_add_i32 s7, s6, 0xfffff001
	s_ashr_i32 s15, s14, 31
	s_cmpk_lt_i32 s14, 0x1000
	s_cselect_b32 s8, s36, s38
	s_cselect_b32 s13, s15, 0
	s_cselect_b32 s12, s14, s7
	s_cselect_b32 s7, s37, s39
	s_lshl_b64 s[12:13], s[12:13], 12
	s_add_u32 s12, s8, s12
	s_addc_u32 s13, s7, s13
	v_lshl_add_u64 v[18:19], s[12:13], 0, v[0:1]
	global_load_dwordx4 v[24:27], v[18:19], off
	s_add_i32 s14, s6, 2
	s_add_i32 s7, s6, 0xfffff002
	s_ashr_i32 s15, s14, 31
	s_cmpk_lt_i32 s14, 0x1000
	s_cselect_b32 s8, s36, s38
	s_cselect_b32 s13, s15, 0
	s_cselect_b32 s12, s14, s7
	s_cselect_b32 s7, s37, s39
	s_lshl_b64 s[12:13], s[12:13], 12
	s_add_u32 s12, s8, s12
	s_addc_u32 s13, s7, s13
	v_lshl_add_u64 v[18:19], s[12:13], 0, v[0:1]
	global_load_dwordx4 v[28:31], v[18:19], off
	s_add_i32 s14, s6, 3
	s_add_i32 s7, s6, 0xfffff003
	s_ashr_i32 s15, s14, 31
	s_cmpk_lt_i32 s14, 0x1000
	s_cselect_b32 s8, s36, s38
	s_cselect_b32 s13, s15, 0
	s_cselect_b32 s12, s14, s7
	s_cselect_b32 s7, s37, s39
	s_lshl_b64 s[12:13], s[12:13], 12
	s_add_u32 s12, s8, s12
	s_addc_u32 s13, s7, s13
	v_lshl_add_u64 v[18:19], s[12:13], 0, v[0:1]
	global_load_dwordx4 v[32:35], v[18:19], off
	s_add_i32 s14, s6, 4
	s_add_i32 s7, s6, 0xfffff004
	s_ashr_i32 s15, s14, 31
	s_cmpk_lt_i32 s14, 0x1000
	s_cselect_b32 s8, s36, s38
	s_cselect_b32 s13, s15, 0
	s_cselect_b32 s12, s14, s7
	s_cselect_b32 s7, s37, s39
	s_lshl_b64 s[12:13], s[12:13], 12
	s_add_u32 s12, s8, s12
	s_addc_u32 s13, s7, s13
	v_lshl_add_u64 v[18:19], s[12:13], 0, v[0:1]
	global_load_dwordx4 v[36:39], v[18:19], off
	s_add_i32 s14, s6, 5
	s_add_i32 s7, s6, 0xfffff005
	s_ashr_i32 s15, s14, 31
	s_cmpk_lt_i32 s14, 0x1000
	s_cselect_b32 s8, s36, s38
	s_cselect_b32 s13, s15, 0
	s_cselect_b32 s12, s14, s7
	s_cselect_b32 s7, s37, s39
	s_lshl_b64 s[12:13], s[12:13], 12
	s_add_u32 s12, s8, s12
	s_addc_u32 s13, s7, s13
	v_lshl_add_u64 v[18:19], s[12:13], 0, v[0:1]
	global_load_dwordx4 v[40:43], v[18:19], off
	s_add_i32 s14, s6, 6
	s_add_i32 s7, s6, 0xfffff006
	s_ashr_i32 s15, s14, 31
	s_cmpk_lt_i32 s14, 0x1000
	s_cselect_b32 s8, s36, s38
	s_cselect_b32 s13, s15, 0
	s_cselect_b32 s12, s14, s7
	s_cselect_b32 s7, s37, s39
	s_lshl_b64 s[12:13], s[12:13], 12
	s_add_u32 s12, s8, s12
	s_addc_u32 s13, s7, s13
	v_lshl_add_u64 v[18:19], s[12:13], 0, v[0:1]
	global_load_dwordx4 v[44:47], v[18:19], off
	s_add_i32 s14, s6, 7
	s_add_i32 s7, s6, 0xfffff007
	s_ashr_i32 s15, s14, 31
	s_cmpk_lt_i32 s14, 0x1000
	s_cselect_b32 s8, s36, s38
	s_cselect_b32 s13, s15, 0
	s_cselect_b32 s12, s14, s7
	s_cselect_b32 s7, s37, s39
	s_lshl_b64 s[12:13], s[12:13], 12
	s_add_u32 s12, s8, s12
	s_addc_u32 s13, s7, s13
	v_lshl_add_u64 v[18:19], s[12:13], 0, v[0:1]
	global_load_dwordx4 v[48:51], v[18:19], off
	s_waitcnt vmcnt(8)
	v_pk_add_f32 v[4:5], v[4:5], 1.0 op_sel_hi:[1,0]
	v_pk_add_f32 v[6:7], v[6:7], 1.0 op_sel_hi:[1,0]
	v_pk_fma_f32 v[8:9], v[4:5], 0, v[8:9] op_sel_hi:[1,0,1]
	v_pk_fma_f32 v[10:11], v[6:7], 0, v[10:11] op_sel_hi:[1,0,1]
	s_add_i32 s14, s6, 0
	s_ashr_i32 s15, s14, 31
	s_lshl_b64 s[12:13], s[14:15], 11
	v_lshl_add_u64 v[16:17], v[2:3], 0, s[12:13]
	s_waitcnt vmcnt(7)
	v_pk_add_f32 v[20:21], v[20:21], 0 op_sel_hi:[1,0]
	v_pk_add_f32 v[22:23], v[22:23], 0 op_sel_hi:[1,0]
	v_pk_fma_f32 v[20:21], v[20:21], v[4:5], v[8:9]
	v_pk_fma_f32 v[22:23], v[22:23], v[6:7], v[10:11]
	v_cvt_pk_bf16_f32 v20, v20, v21
	v_cvt_pk_bf16_f32 v21, v22, v23
	global_store_dwordx2 v[16:17], v[20:21], off
	s_add_i32 s14, s6, 1
	s_ashr_i32 s15, s14, 31
	s_lshl_b64 s[12:13], s[14:15], 11
	v_lshl_add_u64 v[16:17], v[2:3], 0, s[12:13]
	s_waitcnt vmcnt(6)
	v_pk_add_f32 v[24:25], v[24:25], 0 op_sel_hi:[1,0]
	v_pk_add_f32 v[26:27], v[26:27], 0 op_sel_hi:[1,0]
	v_pk_fma_f32 v[24:25], v[24:25], v[4:5], v[8:9]
	v_pk_fma_f32 v[26:27], v[26:27], v[6:7], v[10:11]
	v_cvt_pk_bf16_f32 v24, v24, v25
	v_cvt_pk_bf16_f32 v25, v26, v27
	global_store_dwordx2 v[16:17], v[24:25], off
	s_add_i32 s14, s6, 2
	s_ashr_i32 s15, s14, 31
	s_lshl_b64 s[12:13], s[14:15], 11
	v_lshl_add_u64 v[16:17], v[2:3], 0, s[12:13]
	s_waitcnt vmcnt(5)
	v_pk_add_f32 v[28:29], v[28:29], 0 op_sel_hi:[1,0]
	v_pk_add_f32 v[30:31], v[30:31], 0 op_sel_hi:[1,0]
	v_pk_fma_f32 v[28:29], v[28:29], v[4:5], v[8:9]
	v_pk_fma_f32 v[30:31], v[30:31], v[6:7], v[10:11]
	v_cvt_pk_bf16_f32 v28, v28, v29
	v_cvt_pk_bf16_f32 v29, v30, v31
	global_store_dwordx2 v[16:17], v[28:29], off
	s_add_i32 s14, s6, 3
	s_ashr_i32 s15, s14, 31
	s_lshl_b64 s[12:13], s[14:15], 11
	v_lshl_add_u64 v[16:17], v[2:3], 0, s[12:13]
	s_waitcnt vmcnt(4)
	v_pk_add_f32 v[32:33], v[32:33], 0 op_sel_hi:[1,0]
	v_pk_add_f32 v[34:35], v[34:35], 0 op_sel_hi:[1,0]
	v_pk_fma_f32 v[32:33], v[32:33], v[4:5], v[8:9]
	v_pk_fma_f32 v[34:35], v[34:35], v[6:7], v[10:11]
	v_cvt_pk_bf16_f32 v32, v32, v33
	v_cvt_pk_bf16_f32 v33, v34, v35
	global_store_dwordx2 v[16:17], v[32:33], off
	s_add_i32 s14, s6, 4
	s_ashr_i32 s15, s14, 31
	s_lshl_b64 s[12:13], s[14:15], 11
	v_lshl_add_u64 v[16:17], v[2:3], 0, s[12:13]
	s_waitcnt vmcnt(3)
	v_pk_add_f32 v[36:37], v[36:37], 0 op_sel_hi:[1,0]
	v_pk_add_f32 v[38:39], v[38:39], 0 op_sel_hi:[1,0]
	v_pk_fma_f32 v[36:37], v[36:37], v[4:5], v[8:9]
	v_pk_fma_f32 v[38:39], v[38:39], v[6:7], v[10:11]
	v_cvt_pk_bf16_f32 v36, v36, v37
	v_cvt_pk_bf16_f32 v37, v38, v39
	global_store_dwordx2 v[16:17], v[36:37], off
	s_add_i32 s14, s6, 5
	s_ashr_i32 s15, s14, 31
	s_lshl_b64 s[12:13], s[14:15], 11
	v_lshl_add_u64 v[16:17], v[2:3], 0, s[12:13]
	s_waitcnt vmcnt(2)
	v_pk_add_f32 v[40:41], v[40:41], 0 op_sel_hi:[1,0]
	v_pk_add_f32 v[42:43], v[42:43], 0 op_sel_hi:[1,0]
	v_pk_fma_f32 v[40:41], v[40:41], v[4:5], v[8:9]
	v_pk_fma_f32 v[42:43], v[42:43], v[6:7], v[10:11]
	v_cvt_pk_bf16_f32 v40, v40, v41
	v_cvt_pk_bf16_f32 v41, v42, v43
	global_store_dwordx2 v[16:17], v[40:41], off
	s_add_i32 s14, s6, 6
	s_ashr_i32 s15, s14, 31
	s_lshl_b64 s[12:13], s[14:15], 11
	v_lshl_add_u64 v[16:17], v[2:3], 0, s[12:13]
	s_waitcnt vmcnt(1)
	v_pk_add_f32 v[44:45], v[44:45], 0 op_sel_hi:[1,0]
	v_pk_add_f32 v[46:47], v[46:47], 0 op_sel_hi:[1,0]
	v_pk_fma_f32 v[44:45], v[44:45], v[4:5], v[8:9]
	v_pk_fma_f32 v[46:47], v[46:47], v[6:7], v[10:11]
	v_cvt_pk_bf16_f32 v44, v44, v45
	v_cvt_pk_bf16_f32 v45, v46, v47
	global_store_dwordx2 v[16:17], v[44:45], off
	s_add_i32 s14, s6, 7
	s_ashr_i32 s15, s14, 31
	s_lshl_b64 s[12:13], s[14:15], 11
	v_lshl_add_u64 v[16:17], v[2:3], 0, s[12:13]
	s_waitcnt vmcnt(0)
	v_pk_add_f32 v[48:49], v[48:49], 0 op_sel_hi:[1,0]
	v_pk_add_f32 v[50:51], v[50:51], 0 op_sel_hi:[1,0]
	v_pk_fma_f32 v[48:49], v[48:49], v[4:5], v[8:9]
	v_pk_fma_f32 v[50:51], v[50:51], v[6:7], v[10:11]
	v_cvt_pk_bf16_f32 v48, v48, v49
	v_cvt_pk_bf16_f32 v49, v50, v51
	global_store_dwordx2 v[16:17], v[48:49], off
	s_add_i32 s10, s10, s64
	s_add_i32 s6, s6, s2
	s_cmpk_gt_i32 s10, 0x3ff
	s_cbranch_scc0 .LBB0_138
